# P12 final RMSNorm loop hand-scheduled (16 row loads in flight, gains in registers, quad DPP shuffle so each store writes 64 contiguous bytes) on top of hand-scheduled P5 and P0 loops
# speedup vs baseline: 1.0034x; 1.0034x over previous
.LBB0_2030:
	s_cmp_gt_i32 s54, 12
	s_cselect_b64 s[2:3], -1, 0
	s_xor_b64 s[0:1], s[0:1], -1
	s_or_b64 s[0:1], s[2:3], s[0:1]
	s_and_b64 vcc, exec, s[0:1]
	s_cbranch_vccnz .LBB0_2036
	s_cmpk_gt_i32 s28, 0x2fff
	s_waitcnt vmcnt(0)
	v_mbcnt_lo_u32_b32 v0, -1, 0
	v_mbcnt_hi_u32_b32 v0, -1, v0
	s_cbranch_scc1 .LBB0_2036
	v_lshrrev_b32_e32 v1, 3, v0
	v_bfe_u32 v2, v0, 2, 1
	v_and_b32_e32 v3, 3, v0
	v_lshlrev_b32_e32 v4, 7, v1
	v_lshl_add_u32 v4, v3, 5, v4
	v_lshlrev_b32_e32 v5, 7, v1
	v_lshl_add_u32 v5, v3, 4, v5
	v_lshl_add_u32 v5, v2, 14, v5
	v_and_b32_e32 v15, 1, v0
	v_cmp_eq_u32_e32 vcc, 1, v15
	v_lshrrev_b32_e32 v6, 1, v1
	v_lshlrev_b32_e32 v6, 15, v6
	v_and_b32_e32 v7, 1, v1
	v_lshl_or_b32 v6, v7, 10, v6
	v_lshl_or_b32 v6, v2, 6, v6
	v_lshl_or_b32 v6, v3, 4, v6
	v_lshlrev_b32_e32 v7, 3, v2
	v_mov_b32_e32 v14, 0x358637bd
	s_add_u32 s8, s30, 0x1000
	s_addc_u32 s9, s31, 0
	s_add_u32 s10, s30, 0x2000
	s_addc_u32 s11, s31, 0
	s_add_u32 s12, s30, 0x3000
	s_addc_u32 s13, s31, 0
	global_load_dwordx4 v[100:103], v4, s[30:31]
	global_load_dwordx4 v[104:107], v4, s[30:31] offset:16
	global_load_dwordx4 v[108:111], v4, s[30:31] offset:1024
	global_load_dwordx4 v[112:115], v4, s[30:31] offset:1040
	global_load_dwordx4 v[116:119], v4, s[30:31] offset:2048
	global_load_dwordx4 v[120:123], v4, s[30:31] offset:2064
	global_load_dwordx4 v[124:127], v4, s[30:31] offset:3072
	global_load_dwordx4 v[128:131], v4, s[30:31] offset:3088
	global_load_dwordx4 v[132:135], v4, s[8:9]
	global_load_dwordx4 v[136:139], v4, s[8:9] offset:16
	global_load_dwordx4 v[140:143], v4, s[8:9] offset:1024
	global_load_dwordx4 v[144:147], v4, s[8:9] offset:1040
	global_load_dwordx4 v[148:151], v4, s[8:9] offset:2048
	global_load_dwordx4 v[152:155], v4, s[8:9] offset:2064
	global_load_dwordx4 v[156:159], v4, s[8:9] offset:3072
	global_load_dwordx4 v[160:163], v4, s[8:9] offset:3088
	global_load_dwordx4 v[164:167], v4, s[10:11]
	global_load_dwordx4 v[168:171], v4, s[10:11] offset:16
	global_load_dwordx4 v[172:175], v4, s[10:11] offset:1024
	global_load_dwordx4 v[176:179], v4, s[10:11] offset:1040
	global_load_dwordx4 v[180:183], v4, s[10:11] offset:2048
	global_load_dwordx4 v[184:187], v4, s[10:11] offset:2064
	global_load_dwordx4 v[188:191], v4, s[10:11] offset:3072
	global_load_dwordx4 v[192:195], v4, s[10:11] offset:3088
	global_load_dwordx4 v[196:199], v4, s[12:13]
	global_load_dwordx4 v[200:203], v4, s[12:13] offset:16
	global_load_dwordx4 v[204:207], v4, s[12:13] offset:1024
	global_load_dwordx4 v[208:211], v4, s[12:13] offset:1040
	global_load_dwordx4 v[212:215], v4, s[12:13] offset:2048
	global_load_dwordx4 v[216:219], v4, s[12:13] offset:2064
	global_load_dwordx4 v[220:223], v4, s[12:13] offset:3072
	global_load_dwordx4 v[224:227], v4, s[12:13] offset:3088
.Lp12_row:
	s_lshr_b32 s0, s28, 7
	s_lshl_b32 s0, s0, 21
	s_bfe_u32 s1, s28, 0x10006
	s_lshl_b32 s1, s1, 14
	s_or_b32 s0, s0, s1
	s_bfe_u32 s1, s28, 0x30003
	s_lshl_b32 s1, s1, 11
	s_or_b32 s0, s0, s1
	s_and_b32 s1, s28, 7
	s_lshl_b32 s1, s1, 7
	s_or_b32 s0, s0, s1
	s_add_u32 s0, s34, s0
	s_addc_u32 s1, s35, 0
	s_bfe_u32 s2, s28, 0x10002
	s_lshl_b32 s2, s2, 5
	s_lshl_b32 s3, s28, 4
	s_add_u32 s4, s6, s3
	s_addc_u32 s5, s7, 0
	s_lshl_b32 s3, s28, 15
	s_add_u32 s14, s84, s3
	s_addc_u32 s15, s85, 0
	s_add_u32 s16, s14, 0x1000
	s_addc_u32 s17, s15, 0
	s_add_u32 s18, s14, 0x2000
	s_addc_u32 s19, s15, 0
	s_add_u32 s20, s14, 0x3000
	s_addc_u32 s21, s15, 0
	v_xor_b32_e32 v12, s2, v6
	global_load_dwordx2 v[8:9], v7, s[4:5]
	global_load_dwordx4 v[16:19], v12, s[0:1]
	v_add_u32_e32 v229, 0x20000, v12
	global_load_dwordx4 v[20:23], v229, s[0:1]
	v_add_u32_e32 v230, 0x40000, v12
	global_load_dwordx4 v[24:27], v230, s[0:1]
	v_add_u32_e32 v231, 0x60000, v12
	global_load_dwordx4 v[28:31], v231, s[0:1]
	v_add_u32_e32 v232, 0x80000, v12
	global_load_dwordx4 v[32:35], v232, s[0:1]
	v_add_u32_e32 v233, 0xa0000, v12
	global_load_dwordx4 v[36:39], v233, s[0:1]
	v_add_u32_e32 v234, 0xc0000, v12
	global_load_dwordx4 v[40:43], v234, s[0:1]
	v_add_u32_e32 v235, 0xe0000, v12
	global_load_dwordx4 v[44:47], v235, s[0:1]
	v_add_u32_e32 v236, 0x100000, v12
	global_load_dwordx4 v[48:51], v236, s[0:1]
	v_add_u32_e32 v237, 0x120000, v12
	global_load_dwordx4 v[52:55], v237, s[0:1]
	v_add_u32_e32 v238, 0x140000, v12
	global_load_dwordx4 v[56:59], v238, s[0:1]
	v_add_u32_e32 v239, 0x160000, v12
	global_load_dwordx4 v[60:63], v239, s[0:1]
	v_add_u32_e32 v240, 0x180000, v12
	global_load_dwordx4 v[64:67], v240, s[0:1]
	v_add_u32_e32 v241, 0x1a0000, v12
	global_load_dwordx4 v[68:71], v241, s[0:1]
	v_add_u32_e32 v242, 0x1c0000, v12
	global_load_dwordx4 v[72:75], v242, s[0:1]
	v_add_u32_e32 v243, 0x1e0000, v12
	global_load_dwordx4 v[76:79], v243, s[0:1]
	s_waitcnt vmcnt(16)
	v_cvt_f32_u32_e32 v10, v9
	v_cvt_f32_u32_e32 v11, v8
	v_fmac_f32_e32 v11, 0x4f800000, v10
	v_mul_f32_e32 v10, 0x37800000, v11
	v_fmamk_f32 v10, v10, 0x39800000, v14
	v_rsq_f32_e32 v10, v10
	s_nop 1
	v_mov_b32_e32 v11, v10
	s_waitcnt vmcnt(15)
	v_lshlrev_b32_e32 v80, 16, v16
	v_and_b32_e32 v81, 0xffff0000, v16
	v_lshlrev_b32_e32 v82, 16, v17
	v_and_b32_e32 v83, 0xffff0000, v17
	v_lshlrev_b32_e32 v84, 16, v18
	v_and_b32_e32 v85, 0xffff0000, v18
	v_lshlrev_b32_e32 v86, 16, v19
	v_and_b32_e32 v87, 0xffff0000, v19
	v_pk_mul_f32 v[80:81], v[10:11], v[80:81]
	v_pk_mul_f32 v[82:83], v[10:11], v[82:83]
	v_pk_mul_f32 v[84:85], v[10:11], v[84:85]
	v_pk_mul_f32 v[86:87], v[10:11], v[86:87]
	v_pk_mul_f32 v[80:81], v[100:101], v[80:81]
	v_pk_mul_f32 v[82:83], v[102:103], v[82:83]
	v_pk_mul_f32 v[84:85], v[104:105], v[84:85]
	v_pk_mul_f32 v[86:87], v[106:107], v[86:87]
	s_nop 1
	v_mov_b32_dpp v244, v80 quad_perm:[0,0,1,1] row_mask:0xf bank_mask:0xf
	v_mov_b32_dpp v15, v84 quad_perm:[0,0,1,1] row_mask:0xf bank_mask:0xf
	v_cndmask_b32_e32 v244, v244, v15, vcc
	v_mov_b32_dpp v245, v81 quad_perm:[0,0,1,1] row_mask:0xf bank_mask:0xf
	v_mov_b32_dpp v15, v85 quad_perm:[0,0,1,1] row_mask:0xf bank_mask:0xf
	v_cndmask_b32_e32 v245, v245, v15, vcc
	v_mov_b32_dpp v246, v82 quad_perm:[0,0,1,1] row_mask:0xf bank_mask:0xf
	v_mov_b32_dpp v15, v86 quad_perm:[0,0,1,1] row_mask:0xf bank_mask:0xf
	v_cndmask_b32_e32 v246, v246, v15, vcc
	v_mov_b32_dpp v247, v83 quad_perm:[0,0,1,1] row_mask:0xf bank_mask:0xf
	v_mov_b32_dpp v15, v87 quad_perm:[0,0,1,1] row_mask:0xf bank_mask:0xf
	v_cndmask_b32_e32 v247, v247, v15, vcc
	v_mov_b32_dpp v248, v80 quad_perm:[2,2,3,3] row_mask:0xf bank_mask:0xf
	v_mov_b32_dpp v15, v84 quad_perm:[2,2,3,3] row_mask:0xf bank_mask:0xf
	v_cndmask_b32_e32 v248, v248, v15, vcc
	v_mov_b32_dpp v249, v81 quad_perm:[2,2,3,3] row_mask:0xf bank_mask:0xf
	v_mov_b32_dpp v15, v85 quad_perm:[2,2,3,3] row_mask:0xf bank_mask:0xf
	v_cndmask_b32_e32 v249, v249, v15, vcc
	v_mov_b32_dpp v250, v82 quad_perm:[2,2,3,3] row_mask:0xf bank_mask:0xf
	v_mov_b32_dpp v15, v86 quad_perm:[2,2,3,3] row_mask:0xf bank_mask:0xf
	v_cndmask_b32_e32 v250, v250, v15, vcc
	v_mov_b32_dpp v251, v83 quad_perm:[2,2,3,3] row_mask:0xf bank_mask:0xf
	v_mov_b32_dpp v15, v87 quad_perm:[2,2,3,3] row_mask:0xf bank_mask:0xf
	v_cndmask_b32_e32 v251, v251, v15, vcc
	global_store_dwordx4 v5, v[244:247], s[14:15]
	global_store_dwordx4 v5, v[248:251], s[14:15] offset:64
	s_waitcnt vmcnt(16)
	v_lshlrev_b32_e32 v88, 16, v20
	v_and_b32_e32 v89, 0xffff0000, v20
	v_lshlrev_b32_e32 v90, 16, v21
	v_and_b32_e32 v91, 0xffff0000, v21
	v_lshlrev_b32_e32 v92, 16, v22
	v_and_b32_e32 v93, 0xffff0000, v22
	v_lshlrev_b32_e32 v94, 16, v23
	v_and_b32_e32 v95, 0xffff0000, v23
	v_pk_mul_f32 v[88:89], v[10:11], v[88:89]
	v_pk_mul_f32 v[90:91], v[10:11], v[90:91]
	v_pk_mul_f32 v[92:93], v[10:11], v[92:93]
	v_pk_mul_f32 v[94:95], v[10:11], v[94:95]
	v_pk_mul_f32 v[88:89], v[108:109], v[88:89]
	v_pk_mul_f32 v[90:91], v[110:111], v[90:91]
	v_pk_mul_f32 v[92:93], v[112:113], v[92:93]
	v_pk_mul_f32 v[94:95], v[114:115], v[94:95]
	s_nop 1
	v_mov_b32_dpp v244, v88 quad_perm:[0,0,1,1] row_mask:0xf bank_mask:0xf
	v_mov_b32_dpp v15, v92 quad_perm:[0,0,1,1] row_mask:0xf bank_mask:0xf
	v_cndmask_b32_e32 v244, v244, v15, vcc
	v_mov_b32_dpp v245, v89 quad_perm:[0,0,1,1] row_mask:0xf bank_mask:0xf
	v_mov_b32_dpp v15, v93 quad_perm:[0,0,1,1] row_mask:0xf bank_mask:0xf
	v_cndmask_b32_e32 v245, v245, v15, vcc
	v_mov_b32_dpp v246, v90 quad_perm:[0,0,1,1] row_mask:0xf bank_mask:0xf
	v_mov_b32_dpp v15, v94 quad_perm:[0,0,1,1] row_mask:0xf bank_mask:0xf
	v_cndmask_b32_e32 v246, v246, v15, vcc
	v_mov_b32_dpp v247, v91 quad_perm:[0,0,1,1] row_mask:0xf bank_mask:0xf
	v_mov_b32_dpp v15, v95 quad_perm:[0,0,1,1] row_mask:0xf bank_mask:0xf
	v_cndmask_b32_e32 v247, v247, v15, vcc
	v_mov_b32_dpp v248, v88 quad_perm:[2,2,3,3] row_mask:0xf bank_mask:0xf
	v_mov_b32_dpp v15, v92 quad_perm:[2,2,3,3] row_mask:0xf bank_mask:0xf
	v_cndmask_b32_e32 v248, v248, v15, vcc
	v_mov_b32_dpp v249, v89 quad_perm:[2,2,3,3] row_mask:0xf bank_mask:0xf
	v_mov_b32_dpp v15, v93 quad_perm:[2,2,3,3] row_mask:0xf bank_mask:0xf
	v_cndmask_b32_e32 v249, v249, v15, vcc
	v_mov_b32_dpp v250, v90 quad_perm:[2,2,3,3] row_mask:0xf bank_mask:0xf
	v_mov_b32_dpp v15, v94 quad_perm:[2,2,3,3] row_mask:0xf bank_mask:0xf
	v_cndmask_b32_e32 v250, v250, v15, vcc
	v_mov_b32_dpp v251, v91 quad_perm:[2,2,3,3] row_mask:0xf bank_mask:0xf
	v_mov_b32_dpp v15, v95 quad_perm:[2,2,3,3] row_mask:0xf bank_mask:0xf
	v_cndmask_b32_e32 v251, v251, v15, vcc
	global_store_dwordx4 v5, v[244:247], s[14:15] offset:1024
	global_store_dwordx4 v5, v[248:251], s[14:15] offset:1088
	s_waitcnt vmcnt(17)
	v_lshlrev_b32_e32 v80, 16, v24
	v_and_b32_e32 v81, 0xffff0000, v24
	v_lshlrev_b32_e32 v82, 16, v25
	v_and_b32_e32 v83, 0xffff0000, v25
	v_lshlrev_b32_e32 v84, 16, v26
	v_and_b32_e32 v85, 0xffff0000, v26
	v_lshlrev_b32_e32 v86, 16, v27
	v_and_b32_e32 v87, 0xffff0000, v27
	v_pk_mul_f32 v[80:81], v[10:11], v[80:81]
	v_pk_mul_f32 v[82:83], v[10:11], v[82:83]
	v_pk_mul_f32 v[84:85], v[10:11], v[84:85]
	v_pk_mul_f32 v[86:87], v[10:11], v[86:87]
	v_pk_mul_f32 v[80:81], v[116:117], v[80:81]
	v_pk_mul_f32 v[82:83], v[118:119], v[82:83]
	v_pk_mul_f32 v[84:85], v[120:121], v[84:85]
	v_pk_mul_f32 v[86:87], v[122:123], v[86:87]
	s_nop 1
	v_mov_b32_dpp v244, v80 quad_perm:[0,0,1,1] row_mask:0xf bank_mask:0xf
	v_mov_b32_dpp v15, v84 quad_perm:[0,0,1,1] row_mask:0xf bank_mask:0xf
	v_cndmask_b32_e32 v244, v244, v15, vcc
	v_mov_b32_dpp v245, v81 quad_perm:[0,0,1,1] row_mask:0xf bank_mask:0xf
	v_mov_b32_dpp v15, v85 quad_perm:[0,0,1,1] row_mask:0xf bank_mask:0xf
	v_cndmask_b32_e32 v245, v245, v15, vcc
	v_mov_b32_dpp v246, v82 quad_perm:[0,0,1,1] row_mask:0xf bank_mask:0xf
	v_mov_b32_dpp v15, v86 quad_perm:[0,0,1,1] row_mask:0xf bank_mask:0xf
	v_cndmask_b32_e32 v246, v246, v15, vcc
	v_mov_b32_dpp v247, v83 quad_perm:[0,0,1,1] row_mask:0xf bank_mask:0xf
	v_mov_b32_dpp v15, v87 quad_perm:[0,0,1,1] row_mask:0xf bank_mask:0xf
	v_cndmask_b32_e32 v247, v247, v15, vcc
	v_mov_b32_dpp v248, v80 quad_perm:[2,2,3,3] row_mask:0xf bank_mask:0xf
	v_mov_b32_dpp v15, v84 quad_perm:[2,2,3,3] row_mask:0xf bank_mask:0xf
	v_cndmask_b32_e32 v248, v248, v15, vcc
	v_mov_b32_dpp v249, v81 quad_perm:[2,2,3,3] row_mask:0xf bank_mask:0xf
	v_mov_b32_dpp v15, v85 quad_perm:[2,2,3,3] row_mask:0xf bank_mask:0xf
	v_cndmask_b32_e32 v249, v249, v15, vcc
	v_mov_b32_dpp v250, v82 quad_perm:[2,2,3,3] row_mask:0xf bank_mask:0xf
	v_mov_b32_dpp v15, v86 quad_perm:[2,2,3,3] row_mask:0xf bank_mask:0xf
	v_cndmask_b32_e32 v250, v250, v15, vcc
	v_mov_b32_dpp v251, v83 quad_perm:[2,2,3,3] row_mask:0xf bank_mask:0xf
	v_mov_b32_dpp v15, v87 quad_perm:[2,2,3,3] row_mask:0xf bank_mask:0xf
	v_cndmask_b32_e32 v251, v251, v15, vcc
	global_store_dwordx4 v5, v[244:247], s[14:15] offset:2048
	global_store_dwordx4 v5, v[248:251], s[14:15] offset:2112
	s_waitcnt vmcnt(18)
	v_lshlrev_b32_e32 v88, 16, v28
	v_and_b32_e32 v89, 0xffff0000, v28
	v_lshlrev_b32_e32 v90, 16, v29
	v_and_b32_e32 v91, 0xffff0000, v29
	v_lshlrev_b32_e32 v92, 16, v30
	v_and_b32_e32 v93, 0xffff0000, v30
	v_lshlrev_b32_e32 v94, 16, v31
	v_and_b32_e32 v95, 0xffff0000, v31
	v_pk_mul_f32 v[88:89], v[10:11], v[88:89]
	v_pk_mul_f32 v[90:91], v[10:11], v[90:91]
	v_pk_mul_f32 v[92:93], v[10:11], v[92:93]
	v_pk_mul_f32 v[94:95], v[10:11], v[94:95]
	v_pk_mul_f32 v[88:89], v[124:125], v[88:89]
	v_pk_mul_f32 v[90:91], v[126:127], v[90:91]
	v_pk_mul_f32 v[92:93], v[128:129], v[92:93]
	v_pk_mul_f32 v[94:95], v[130:131], v[94:95]
	s_nop 1
	v_mov_b32_dpp v244, v88 quad_perm:[0,0,1,1] row_mask:0xf bank_mask:0xf
	v_mov_b32_dpp v15, v92 quad_perm:[0,0,1,1] row_mask:0xf bank_mask:0xf
	v_cndmask_b32_e32 v244, v244, v15, vcc
	v_mov_b32_dpp v245, v89 quad_perm:[0,0,1,1] row_mask:0xf bank_mask:0xf
	v_mov_b32_dpp v15, v93 quad_perm:[0,0,1,1] row_mask:0xf bank_mask:0xf
	v_cndmask_b32_e32 v245, v245, v15, vcc
	v_mov_b32_dpp v246, v90 quad_perm:[0,0,1,1] row_mask:0xf bank_mask:0xf
	v_mov_b32_dpp v15, v94 quad_perm:[0,0,1,1] row_mask:0xf bank_mask:0xf
	v_cndmask_b32_e32 v246, v246, v15, vcc
	v_mov_b32_dpp v247, v91 quad_perm:[0,0,1,1] row_mask:0xf bank_mask:0xf
	v_mov_b32_dpp v15, v95 quad_perm:[0,0,1,1] row_mask:0xf bank_mask:0xf
	v_cndmask_b32_e32 v247, v247, v15, vcc
	v_mov_b32_dpp v248, v88 quad_perm:[2,2,3,3] row_mask:0xf bank_mask:0xf
	v_mov_b32_dpp v15, v92 quad_perm:[2,2,3,3] row_mask:0xf bank_mask:0xf
	v_cndmask_b32_e32 v248, v248, v15, vcc
	v_mov_b32_dpp v249, v89 quad_perm:[2,2,3,3] row_mask:0xf bank_mask:0xf
	v_mov_b32_dpp v15, v93 quad_perm:[2,2,3,3] row_mask:0xf bank_mask:0xf
	v_cndmask_b32_e32 v249, v249, v15, vcc
	v_mov_b32_dpp v250, v90 quad_perm:[2,2,3,3] row_mask:0xf bank_mask:0xf
	v_mov_b32_dpp v15, v94 quad_perm:[2,2,3,3] row_mask:0xf bank_mask:0xf
	v_cndmask_b32_e32 v250, v250, v15, vcc
	v_mov_b32_dpp v251, v91 quad_perm:[2,2,3,3] row_mask:0xf bank_mask:0xf
	v_mov_b32_dpp v15, v95 quad_perm:[2,2,3,3] row_mask:0xf bank_mask:0xf
	v_cndmask_b32_e32 v251, v251, v15, vcc
	global_store_dwordx4 v5, v[244:247], s[14:15] offset:3072
	global_store_dwordx4 v5, v[248:251], s[14:15] offset:3136
	s_waitcnt vmcnt(19)
	v_lshlrev_b32_e32 v80, 16, v32
	v_and_b32_e32 v81, 0xffff0000, v32
	v_lshlrev_b32_e32 v82, 16, v33
	v_and_b32_e32 v83, 0xffff0000, v33
	v_lshlrev_b32_e32 v84, 16, v34
	v_and_b32_e32 v85, 0xffff0000, v34
	v_lshlrev_b32_e32 v86, 16, v35
	v_and_b32_e32 v87, 0xffff0000, v35
	v_pk_mul_f32 v[80:81], v[10:11], v[80:81]
	v_pk_mul_f32 v[82:83], v[10:11], v[82:83]
	v_pk_mul_f32 v[84:85], v[10:11], v[84:85]
	v_pk_mul_f32 v[86:87], v[10:11], v[86:87]
	v_pk_mul_f32 v[80:81], v[132:133], v[80:81]
	v_pk_mul_f32 v[82:83], v[134:135], v[82:83]
	v_pk_mul_f32 v[84:85], v[136:137], v[84:85]
	v_pk_mul_f32 v[86:87], v[138:139], v[86:87]
	s_nop 1
	v_mov_b32_dpp v244, v80 quad_perm:[0,0,1,1] row_mask:0xf bank_mask:0xf
	v_mov_b32_dpp v15, v84 quad_perm:[0,0,1,1] row_mask:0xf bank_mask:0xf
	v_cndmask_b32_e32 v244, v244, v15, vcc
	v_mov_b32_dpp v245, v81 quad_perm:[0,0,1,1] row_mask:0xf bank_mask:0xf
	v_mov_b32_dpp v15, v85 quad_perm:[0,0,1,1] row_mask:0xf bank_mask:0xf
	v_cndmask_b32_e32 v245, v245, v15, vcc
	v_mov_b32_dpp v246, v82 quad_perm:[0,0,1,1] row_mask:0xf bank_mask:0xf
	v_mov_b32_dpp v15, v86 quad_perm:[0,0,1,1] row_mask:0xf bank_mask:0xf
	v_cndmask_b32_e32 v246, v246, v15, vcc
	v_mov_b32_dpp v247, v83 quad_perm:[0,0,1,1] row_mask:0xf bank_mask:0xf
	v_mov_b32_dpp v15, v87 quad_perm:[0,0,1,1] row_mask:0xf bank_mask:0xf
	v_cndmask_b32_e32 v247, v247, v15, vcc
	v_mov_b32_dpp v248, v80 quad_perm:[2,2,3,3] row_mask:0xf bank_mask:0xf
	v_mov_b32_dpp v15, v84 quad_perm:[2,2,3,3] row_mask:0xf bank_mask:0xf
	v_cndmask_b32_e32 v248, v248, v15, vcc
	v_mov_b32_dpp v249, v81 quad_perm:[2,2,3,3] row_mask:0xf bank_mask:0xf
	v_mov_b32_dpp v15, v85 quad_perm:[2,2,3,3] row_mask:0xf bank_mask:0xf
	v_cndmask_b32_e32 v249, v249, v15, vcc
	v_mov_b32_dpp v250, v82 quad_perm:[2,2,3,3] row_mask:0xf bank_mask:0xf
	v_mov_b32_dpp v15, v86 quad_perm:[2,2,3,3] row_mask:0xf bank_mask:0xf
	v_cndmask_b32_e32 v250, v250, v15, vcc
	v_mov_b32_dpp v251, v83 quad_perm:[2,2,3,3] row_mask:0xf bank_mask:0xf
	v_mov_b32_dpp v15, v87 quad_perm:[2,2,3,3] row_mask:0xf bank_mask:0xf
	v_cndmask_b32_e32 v251, v251, v15, vcc
	global_store_dwordx4 v5, v[244:247], s[16:17]
	global_store_dwordx4 v5, v[248:251], s[16:17] offset:64
	s_waitcnt vmcnt(20)
	v_lshlrev_b32_e32 v88, 16, v36
	v_and_b32_e32 v89, 0xffff0000, v36
	v_lshlrev_b32_e32 v90, 16, v37
	v_and_b32_e32 v91, 0xffff0000, v37
	v_lshlrev_b32_e32 v92, 16, v38
	v_and_b32_e32 v93, 0xffff0000, v38
	v_lshlrev_b32_e32 v94, 16, v39
	v_and_b32_e32 v95, 0xffff0000, v39
	v_pk_mul_f32 v[88:89], v[10:11], v[88:89]
	v_pk_mul_f32 v[90:91], v[10:11], v[90:91]
	v_pk_mul_f32 v[92:93], v[10:11], v[92:93]
	v_pk_mul_f32 v[94:95], v[10:11], v[94:95]
	v_pk_mul_f32 v[88:89], v[140:141], v[88:89]
	v_pk_mul_f32 v[90:91], v[142:143], v[90:91]
	v_pk_mul_f32 v[92:93], v[144:145], v[92:93]
	v_pk_mul_f32 v[94:95], v[146:147], v[94:95]
	s_nop 1
	v_mov_b32_dpp v244, v88 quad_perm:[0,0,1,1] row_mask:0xf bank_mask:0xf
	v_mov_b32_dpp v15, v92 quad_perm:[0,0,1,1] row_mask:0xf bank_mask:0xf
	v_cndmask_b32_e32 v244, v244, v15, vcc
	v_mov_b32_dpp v245, v89 quad_perm:[0,0,1,1] row_mask:0xf bank_mask:0xf
	v_mov_b32_dpp v15, v93 quad_perm:[0,0,1,1] row_mask:0xf bank_mask:0xf
	v_cndmask_b32_e32 v245, v245, v15, vcc
	v_mov_b32_dpp v246, v90 quad_perm:[0,0,1,1] row_mask:0xf bank_mask:0xf
	v_mov_b32_dpp v15, v94 quad_perm:[0,0,1,1] row_mask:0xf bank_mask:0xf
	v_cndmask_b32_e32 v246, v246, v15, vcc
	v_mov_b32_dpp v247, v91 quad_perm:[0,0,1,1] row_mask:0xf bank_mask:0xf
	v_mov_b32_dpp v15, v95 quad_perm:[0,0,1,1] row_mask:0xf bank_mask:0xf
	v_cndmask_b32_e32 v247, v247, v15, vcc
	v_mov_b32_dpp v248, v88 quad_perm:[2,2,3,3] row_mask:0xf bank_mask:0xf
	v_mov_b32_dpp v15, v92 quad_perm:[2,2,3,3] row_mask:0xf bank_mask:0xf
	v_cndmask_b32_e32 v248, v248, v15, vcc
	v_mov_b32_dpp v249, v89 quad_perm:[2,2,3,3] row_mask:0xf bank_mask:0xf
	v_mov_b32_dpp v15, v93 quad_perm:[2,2,3,3] row_mask:0xf bank_mask:0xf
	v_cndmask_b32_e32 v249, v249, v15, vcc
	v_mov_b32_dpp v250, v90 quad_perm:[2,2,3,3] row_mask:0xf bank_mask:0xf
	v_mov_b32_dpp v15, v94 quad_perm:[2,2,3,3] row_mask:0xf bank_mask:0xf
	v_cndmask_b32_e32 v250, v250, v15, vcc
	v_mov_b32_dpp v251, v91 quad_perm:[2,2,3,3] row_mask:0xf bank_mask:0xf
	v_mov_b32_dpp v15, v95 quad_perm:[2,2,3,3] row_mask:0xf bank_mask:0xf
	v_cndmask_b32_e32 v251, v251, v15, vcc
	global_store_dwordx4 v5, v[244:247], s[16:17] offset:1024
	global_store_dwordx4 v5, v[248:251], s[16:17] offset:1088
	s_waitcnt vmcnt(21)
	v_lshlrev_b32_e32 v80, 16, v40
	v_and_b32_e32 v81, 0xffff0000, v40
	v_lshlrev_b32_e32 v82, 16, v41
	v_and_b32_e32 v83, 0xffff0000, v41
	v_lshlrev_b32_e32 v84, 16, v42
	v_and_b32_e32 v85, 0xffff0000, v42
	v_lshlrev_b32_e32 v86, 16, v43
	v_and_b32_e32 v87, 0xffff0000, v43
	v_pk_mul_f32 v[80:81], v[10:11], v[80:81]
	v_pk_mul_f32 v[82:83], v[10:11], v[82:83]
	v_pk_mul_f32 v[84:85], v[10:11], v[84:85]
	v_pk_mul_f32 v[86:87], v[10:11], v[86:87]
	v_pk_mul_f32 v[80:81], v[148:149], v[80:81]
	v_pk_mul_f32 v[82:83], v[150:151], v[82:83]
	v_pk_mul_f32 v[84:85], v[152:153], v[84:85]
	v_pk_mul_f32 v[86:87], v[154:155], v[86:87]
	s_nop 1
	v_mov_b32_dpp v244, v80 quad_perm:[0,0,1,1] row_mask:0xf bank_mask:0xf
	v_mov_b32_dpp v15, v84 quad_perm:[0,0,1,1] row_mask:0xf bank_mask:0xf
	v_cndmask_b32_e32 v244, v244, v15, vcc
	v_mov_b32_dpp v245, v81 quad_perm:[0,0,1,1] row_mask:0xf bank_mask:0xf
	v_mov_b32_dpp v15, v85 quad_perm:[0,0,1,1] row_mask:0xf bank_mask:0xf
	v_cndmask_b32_e32 v245, v245, v15, vcc
	v_mov_b32_dpp v246, v82 quad_perm:[0,0,1,1] row_mask:0xf bank_mask:0xf
	v_mov_b32_dpp v15, v86 quad_perm:[0,0,1,1] row_mask:0xf bank_mask:0xf
	v_cndmask_b32_e32 v246, v246, v15, vcc
	v_mov_b32_dpp v247, v83 quad_perm:[0,0,1,1] row_mask:0xf bank_mask:0xf
	v_mov_b32_dpp v15, v87 quad_perm:[0,0,1,1] row_mask:0xf bank_mask:0xf
	v_cndmask_b32_e32 v247, v247, v15, vcc
	v_mov_b32_dpp v248, v80 quad_perm:[2,2,3,3] row_mask:0xf bank_mask:0xf
	v_mov_b32_dpp v15, v84 quad_perm:[2,2,3,3] row_mask:0xf bank_mask:0xf
	v_cndmask_b32_e32 v248, v248, v15, vcc
	v_mov_b32_dpp v249, v81 quad_perm:[2,2,3,3] row_mask:0xf bank_mask:0xf
	v_mov_b32_dpp v15, v85 quad_perm:[2,2,3,3] row_mask:0xf bank_mask:0xf
	v_cndmask_b32_e32 v249, v249, v15, vcc
	v_mov_b32_dpp v250, v82 quad_perm:[2,2,3,3] row_mask:0xf bank_mask:0xf
	v_mov_b32_dpp v15, v86 quad_perm:[2,2,3,3] row_mask:0xf bank_mask:0xf
	v_cndmask_b32_e32 v250, v250, v15, vcc
	v_mov_b32_dpp v251, v83 quad_perm:[2,2,3,3] row_mask:0xf bank_mask:0xf
	v_mov_b32_dpp v15, v87 quad_perm:[2,2,3,3] row_mask:0xf bank_mask:0xf
	v_cndmask_b32_e32 v251, v251, v15, vcc
	global_store_dwordx4 v5, v[244:247], s[16:17] offset:2048
	global_store_dwordx4 v5, v[248:251], s[16:17] offset:2112
	s_waitcnt vmcnt(22)
	v_lshlrev_b32_e32 v88, 16, v44
	v_and_b32_e32 v89, 0xffff0000, v44
	v_lshlrev_b32_e32 v90, 16, v45
	v_and_b32_e32 v91, 0xffff0000, v45
	v_lshlrev_b32_e32 v92, 16, v46
	v_and_b32_e32 v93, 0xffff0000, v46
	v_lshlrev_b32_e32 v94, 16, v47
	v_and_b32_e32 v95, 0xffff0000, v47
	v_pk_mul_f32 v[88:89], v[10:11], v[88:89]
	v_pk_mul_f32 v[90:91], v[10:11], v[90:91]
	v_pk_mul_f32 v[92:93], v[10:11], v[92:93]
	v_pk_mul_f32 v[94:95], v[10:11], v[94:95]
	v_pk_mul_f32 v[88:89], v[156:157], v[88:89]
	v_pk_mul_f32 v[90:91], v[158:159], v[90:91]
	v_pk_mul_f32 v[92:93], v[160:161], v[92:93]
	v_pk_mul_f32 v[94:95], v[162:163], v[94:95]
	s_nop 1
	v_mov_b32_dpp v244, v88 quad_perm:[0,0,1,1] row_mask:0xf bank_mask:0xf
	v_mov_b32_dpp v15, v92 quad_perm:[0,0,1,1] row_mask:0xf bank_mask:0xf
	v_cndmask_b32_e32 v244, v244, v15, vcc
	v_mov_b32_dpp v245, v89 quad_perm:[0,0,1,1] row_mask:0xf bank_mask:0xf
	v_mov_b32_dpp v15, v93 quad_perm:[0,0,1,1] row_mask:0xf bank_mask:0xf
	v_cndmask_b32_e32 v245, v245, v15, vcc
	v_mov_b32_dpp v246, v90 quad_perm:[0,0,1,1] row_mask:0xf bank_mask:0xf
	v_mov_b32_dpp v15, v94 quad_perm:[0,0,1,1] row_mask:0xf bank_mask:0xf
	v_cndmask_b32_e32 v246, v246, v15, vcc
	v_mov_b32_dpp v247, v91 quad_perm:[0,0,1,1] row_mask:0xf bank_mask:0xf
	v_mov_b32_dpp v15, v95 quad_perm:[0,0,1,1] row_mask:0xf bank_mask:0xf
	v_cndmask_b32_e32 v247, v247, v15, vcc
	v_mov_b32_dpp v248, v88 quad_perm:[2,2,3,3] row_mask:0xf bank_mask:0xf
	v_mov_b32_dpp v15, v92 quad_perm:[2,2,3,3] row_mask:0xf bank_mask:0xf
	v_cndmask_b32_e32 v248, v248, v15, vcc
	v_mov_b32_dpp v249, v89 quad_perm:[2,2,3,3] row_mask:0xf bank_mask:0xf
	v_mov_b32_dpp v15, v93 quad_perm:[2,2,3,3] row_mask:0xf bank_mask:0xf
	v_cndmask_b32_e32 v249, v249, v15, vcc
	v_mov_b32_dpp v250, v90 quad_perm:[2,2,3,3] row_mask:0xf bank_mask:0xf
	v_mov_b32_dpp v15, v94 quad_perm:[2,2,3,3] row_mask:0xf bank_mask:0xf
	v_cndmask_b32_e32 v250, v250, v15, vcc
	v_mov_b32_dpp v251, v91 quad_perm:[2,2,3,3] row_mask:0xf bank_mask:0xf
	v_mov_b32_dpp v15, v95 quad_perm:[2,2,3,3] row_mask:0xf bank_mask:0xf
	v_cndmask_b32_e32 v251, v251, v15, vcc
	global_store_dwordx4 v5, v[244:247], s[16:17] offset:3072
	global_store_dwordx4 v5, v[248:251], s[16:17] offset:3136
	s_waitcnt vmcnt(23)
	v_lshlrev_b32_e32 v80, 16, v48
	v_and_b32_e32 v81, 0xffff0000, v48
	v_lshlrev_b32_e32 v82, 16, v49
	v_and_b32_e32 v83, 0xffff0000, v49
	v_lshlrev_b32_e32 v84, 16, v50
	v_and_b32_e32 v85, 0xffff0000, v50
	v_lshlrev_b32_e32 v86, 16, v51
	v_and_b32_e32 v87, 0xffff0000, v51
	v_pk_mul_f32 v[80:81], v[10:11], v[80:81]
	v_pk_mul_f32 v[82:83], v[10:11], v[82:83]
	v_pk_mul_f32 v[84:85], v[10:11], v[84:85]
	v_pk_mul_f32 v[86:87], v[10:11], v[86:87]
	v_pk_mul_f32 v[80:81], v[164:165], v[80:81]
	v_pk_mul_f32 v[82:83], v[166:167], v[82:83]
	v_pk_mul_f32 v[84:85], v[168:169], v[84:85]
	v_pk_mul_f32 v[86:87], v[170:171], v[86:87]
	s_nop 1
	v_mov_b32_dpp v244, v80 quad_perm:[0,0,1,1] row_mask:0xf bank_mask:0xf
	v_mov_b32_dpp v15, v84 quad_perm:[0,0,1,1] row_mask:0xf bank_mask:0xf
	v_cndmask_b32_e32 v244, v244, v15, vcc
	v_mov_b32_dpp v245, v81 quad_perm:[0,0,1,1] row_mask:0xf bank_mask:0xf
	v_mov_b32_dpp v15, v85 quad_perm:[0,0,1,1] row_mask:0xf bank_mask:0xf
	v_cndmask_b32_e32 v245, v245, v15, vcc
	v_mov_b32_dpp v246, v82 quad_perm:[0,0,1,1] row_mask:0xf bank_mask:0xf
	v_mov_b32_dpp v15, v86 quad_perm:[0,0,1,1] row_mask:0xf bank_mask:0xf
	v_cndmask_b32_e32 v246, v246, v15, vcc
	v_mov_b32_dpp v247, v83 quad_perm:[0,0,1,1] row_mask:0xf bank_mask:0xf
	v_mov_b32_dpp v15, v87 quad_perm:[0,0,1,1] row_mask:0xf bank_mask:0xf
	v_cndmask_b32_e32 v247, v247, v15, vcc
	v_mov_b32_dpp v248, v80 quad_perm:[2,2,3,3] row_mask:0xf bank_mask:0xf
	v_mov_b32_dpp v15, v84 quad_perm:[2,2,3,3] row_mask:0xf bank_mask:0xf
	v_cndmask_b32_e32 v248, v248, v15, vcc
	v_mov_b32_dpp v249, v81 quad_perm:[2,2,3,3] row_mask:0xf bank_mask:0xf
	v_mov_b32_dpp v15, v85 quad_perm:[2,2,3,3] row_mask:0xf bank_mask:0xf
	v_cndmask_b32_e32 v249, v249, v15, vcc
	v_mov_b32_dpp v250, v82 quad_perm:[2,2,3,3] row_mask:0xf bank_mask:0xf
	v_mov_b32_dpp v15, v86 quad_perm:[2,2,3,3] row_mask:0xf bank_mask:0xf
	v_cndmask_b32_e32 v250, v250, v15, vcc
	v_mov_b32_dpp v251, v83 quad_perm:[2,2,3,3] row_mask:0xf bank_mask:0xf
	v_mov_b32_dpp v15, v87 quad_perm:[2,2,3,3] row_mask:0xf bank_mask:0xf
	v_cndmask_b32_e32 v251, v251, v15, vcc
	global_store_dwordx4 v5, v[244:247], s[18:19]
	global_store_dwordx4 v5, v[248:251], s[18:19] offset:64
	s_waitcnt vmcnt(24)
	v_lshlrev_b32_e32 v88, 16, v52
	v_and_b32_e32 v89, 0xffff0000, v52
	v_lshlrev_b32_e32 v90, 16, v53
	v_and_b32_e32 v91, 0xffff0000, v53
	v_lshlrev_b32_e32 v92, 16, v54
	v_and_b32_e32 v93, 0xffff0000, v54
	v_lshlrev_b32_e32 v94, 16, v55
	v_and_b32_e32 v95, 0xffff0000, v55
	v_pk_mul_f32 v[88:89], v[10:11], v[88:89]
	v_pk_mul_f32 v[90:91], v[10:11], v[90:91]
	v_pk_mul_f32 v[92:93], v[10:11], v[92:93]
	v_pk_mul_f32 v[94:95], v[10:11], v[94:95]
	v_pk_mul_f32 v[88:89], v[172:173], v[88:89]
	v_pk_mul_f32 v[90:91], v[174:175], v[90:91]
	v_pk_mul_f32 v[92:93], v[176:177], v[92:93]
	v_pk_mul_f32 v[94:95], v[178:179], v[94:95]
	s_nop 1
	v_mov_b32_dpp v244, v88 quad_perm:[0,0,1,1] row_mask:0xf bank_mask:0xf
	v_mov_b32_dpp v15, v92 quad_perm:[0,0,1,1] row_mask:0xf bank_mask:0xf
	v_cndmask_b32_e32 v244, v244, v15, vcc
	v_mov_b32_dpp v245, v89 quad_perm:[0,0,1,1] row_mask:0xf bank_mask:0xf
	v_mov_b32_dpp v15, v93 quad_perm:[0,0,1,1] row_mask:0xf bank_mask:0xf
	v_cndmask_b32_e32 v245, v245, v15, vcc
	v_mov_b32_dpp v246, v90 quad_perm:[0,0,1,1] row_mask:0xf bank_mask:0xf
	v_mov_b32_dpp v15, v94 quad_perm:[0,0,1,1] row_mask:0xf bank_mask:0xf
	v_cndmask_b32_e32 v246, v246, v15, vcc
	v_mov_b32_dpp v247, v91 quad_perm:[0,0,1,1] row_mask:0xf bank_mask:0xf
	v_mov_b32_dpp v15, v95 quad_perm:[0,0,1,1] row_mask:0xf bank_mask:0xf
	v_cndmask_b32_e32 v247, v247, v15, vcc
	v_mov_b32_dpp v248, v88 quad_perm:[2,2,3,3] row_mask:0xf bank_mask:0xf
	v_mov_b32_dpp v15, v92 quad_perm:[2,2,3,3] row_mask:0xf bank_mask:0xf
	v_cndmask_b32_e32 v248, v248, v15, vcc
	v_mov_b32_dpp v249, v89 quad_perm:[2,2,3,3] row_mask:0xf bank_mask:0xf
	v_mov_b32_dpp v15, v93 quad_perm:[2,2,3,3] row_mask:0xf bank_mask:0xf
	v_cndmask_b32_e32 v249, v249, v15, vcc
	v_mov_b32_dpp v250, v90 quad_perm:[2,2,3,3] row_mask:0xf bank_mask:0xf
	v_mov_b32_dpp v15, v94 quad_perm:[2,2,3,3] row_mask:0xf bank_mask:0xf
	v_cndmask_b32_e32 v250, v250, v15, vcc
	v_mov_b32_dpp v251, v91 quad_perm:[2,2,3,3] row_mask:0xf bank_mask:0xf
	v_mov_b32_dpp v15, v95 quad_perm:[2,2,3,3] row_mask:0xf bank_mask:0xf
	v_cndmask_b32_e32 v251, v251, v15, vcc
	global_store_dwordx4 v5, v[244:247], s[18:19] offset:1024
	global_store_dwordx4 v5, v[248:251], s[18:19] offset:1088
	s_waitcnt vmcnt(25)
	v_lshlrev_b32_e32 v80, 16, v56
	v_and_b32_e32 v81, 0xffff0000, v56
	v_lshlrev_b32_e32 v82, 16, v57
	v_and_b32_e32 v83, 0xffff0000, v57
	v_lshlrev_b32_e32 v84, 16, v58
	v_and_b32_e32 v85, 0xffff0000, v58
	v_lshlrev_b32_e32 v86, 16, v59
	v_and_b32_e32 v87, 0xffff0000, v59
	v_pk_mul_f32 v[80:81], v[10:11], v[80:81]
	v_pk_mul_f32 v[82:83], v[10:11], v[82:83]
	v_pk_mul_f32 v[84:85], v[10:11], v[84:85]
	v_pk_mul_f32 v[86:87], v[10:11], v[86:87]
	v_pk_mul_f32 v[80:81], v[180:181], v[80:81]
	v_pk_mul_f32 v[82:83], v[182:183], v[82:83]
	v_pk_mul_f32 v[84:85], v[184:185], v[84:85]
	v_pk_mul_f32 v[86:87], v[186:187], v[86:87]
	s_nop 1
	v_mov_b32_dpp v244, v80 quad_perm:[0,0,1,1] row_mask:0xf bank_mask:0xf
	v_mov_b32_dpp v15, v84 quad_perm:[0,0,1,1] row_mask:0xf bank_mask:0xf
	v_cndmask_b32_e32 v244, v244, v15, vcc
	v_mov_b32_dpp v245, v81 quad_perm:[0,0,1,1] row_mask:0xf bank_mask:0xf
	v_mov_b32_dpp v15, v85 quad_perm:[0,0,1,1] row_mask:0xf bank_mask:0xf
	v_cndmask_b32_e32 v245, v245, v15, vcc
	v_mov_b32_dpp v246, v82 quad_perm:[0,0,1,1] row_mask:0xf bank_mask:0xf
	v_mov_b32_dpp v15, v86 quad_perm:[0,0,1,1] row_mask:0xf bank_mask:0xf
	v_cndmask_b32_e32 v246, v246, v15, vcc
	v_mov_b32_dpp v247, v83 quad_perm:[0,0,1,1] row_mask:0xf bank_mask:0xf
	v_mov_b32_dpp v15, v87 quad_perm:[0,0,1,1] row_mask:0xf bank_mask:0xf
	v_cndmask_b32_e32 v247, v247, v15, vcc
	v_mov_b32_dpp v248, v80 quad_perm:[2,2,3,3] row_mask:0xf bank_mask:0xf
	v_mov_b32_dpp v15, v84 quad_perm:[2,2,3,3] row_mask:0xf bank_mask:0xf
	v_cndmask_b32_e32 v248, v248, v15, vcc
	v_mov_b32_dpp v249, v81 quad_perm:[2,2,3,3] row_mask:0xf bank_mask:0xf
	v_mov_b32_dpp v15, v85 quad_perm:[2,2,3,3] row_mask:0xf bank_mask:0xf
	v_cndmask_b32_e32 v249, v249, v15, vcc
	v_mov_b32_dpp v250, v82 quad_perm:[2,2,3,3] row_mask:0xf bank_mask:0xf
	v_mov_b32_dpp v15, v86 quad_perm:[2,2,3,3] row_mask:0xf bank_mask:0xf
	v_cndmask_b32_e32 v250, v250, v15, vcc
	v_mov_b32_dpp v251, v83 quad_perm:[2,2,3,3] row_mask:0xf bank_mask:0xf
	v_mov_b32_dpp v15, v87 quad_perm:[2,2,3,3] row_mask:0xf bank_mask:0xf
	v_cndmask_b32_e32 v251, v251, v15, vcc
	global_store_dwordx4 v5, v[244:247], s[18:19] offset:2048
	global_store_dwordx4 v5, v[248:251], s[18:19] offset:2112
	s_waitcnt vmcnt(26)
	v_lshlrev_b32_e32 v88, 16, v60
	v_and_b32_e32 v89, 0xffff0000, v60
	v_lshlrev_b32_e32 v90, 16, v61
	v_and_b32_e32 v91, 0xffff0000, v61
	v_lshlrev_b32_e32 v92, 16, v62
	v_and_b32_e32 v93, 0xffff0000, v62
	v_lshlrev_b32_e32 v94, 16, v63
	v_and_b32_e32 v95, 0xffff0000, v63
	v_pk_mul_f32 v[88:89], v[10:11], v[88:89]
	v_pk_mul_f32 v[90:91], v[10:11], v[90:91]
	v_pk_mul_f32 v[92:93], v[10:11], v[92:93]
	v_pk_mul_f32 v[94:95], v[10:11], v[94:95]
	v_pk_mul_f32 v[88:89], v[188:189], v[88:89]
	v_pk_mul_f32 v[90:91], v[190:191], v[90:91]
	v_pk_mul_f32 v[92:93], v[192:193], v[92:93]
	v_pk_mul_f32 v[94:95], v[194:195], v[94:95]
	s_nop 1
	v_mov_b32_dpp v244, v88 quad_perm:[0,0,1,1] row_mask:0xf bank_mask:0xf
	v_mov_b32_dpp v15, v92 quad_perm:[0,0,1,1] row_mask:0xf bank_mask:0xf
	v_cndmask_b32_e32 v244, v244, v15, vcc
	v_mov_b32_dpp v245, v89 quad_perm:[0,0,1,1] row_mask:0xf bank_mask:0xf
	v_mov_b32_dpp v15, v93 quad_perm:[0,0,1,1] row_mask:0xf bank_mask:0xf
	v_cndmask_b32_e32 v245, v245, v15, vcc
	v_mov_b32_dpp v246, v90 quad_perm:[0,0,1,1] row_mask:0xf bank_mask:0xf
	v_mov_b32_dpp v15, v94 quad_perm:[0,0,1,1] row_mask:0xf bank_mask:0xf
	v_cndmask_b32_e32 v246, v246, v15, vcc
	v_mov_b32_dpp v247, v91 quad_perm:[0,0,1,1] row_mask:0xf bank_mask:0xf
	v_mov_b32_dpp v15, v95 quad_perm:[0,0,1,1] row_mask:0xf bank_mask:0xf
	v_cndmask_b32_e32 v247, v247, v15, vcc
	v_mov_b32_dpp v248, v88 quad_perm:[2,2,3,3] row_mask:0xf bank_mask:0xf
	v_mov_b32_dpp v15, v92 quad_perm:[2,2,3,3] row_mask:0xf bank_mask:0xf
	v_cndmask_b32_e32 v248, v248, v15, vcc
	v_mov_b32_dpp v249, v89 quad_perm:[2,2,3,3] row_mask:0xf bank_mask:0xf
	v_mov_b32_dpp v15, v93 quad_perm:[2,2,3,3] row_mask:0xf bank_mask:0xf
	v_cndmask_b32_e32 v249, v249, v15, vcc
	v_mov_b32_dpp v250, v90 quad_perm:[2,2,3,3] row_mask:0xf bank_mask:0xf
	v_mov_b32_dpp v15, v94 quad_perm:[2,2,3,3] row_mask:0xf bank_mask:0xf
	v_cndmask_b32_e32 v250, v250, v15, vcc
	v_mov_b32_dpp v251, v91 quad_perm:[2,2,3,3] row_mask:0xf bank_mask:0xf
	v_mov_b32_dpp v15, v95 quad_perm:[2,2,3,3] row_mask:0xf bank_mask:0xf
	v_cndmask_b32_e32 v251, v251, v15, vcc
	global_store_dwordx4 v5, v[244:247], s[18:19] offset:3072
	global_store_dwordx4 v5, v[248:251], s[18:19] offset:3136
	s_waitcnt vmcnt(27)
	v_lshlrev_b32_e32 v80, 16, v64
	v_and_b32_e32 v81, 0xffff0000, v64
	v_lshlrev_b32_e32 v82, 16, v65
	v_and_b32_e32 v83, 0xffff0000, v65
	v_lshlrev_b32_e32 v84, 16, v66
	v_and_b32_e32 v85, 0xffff0000, v66
	v_lshlrev_b32_e32 v86, 16, v67
	v_and_b32_e32 v87, 0xffff0000, v67
	v_pk_mul_f32 v[80:81], v[10:11], v[80:81]
	v_pk_mul_f32 v[82:83], v[10:11], v[82:83]
	v_pk_mul_f32 v[84:85], v[10:11], v[84:85]
	v_pk_mul_f32 v[86:87], v[10:11], v[86:87]
	v_pk_mul_f32 v[80:81], v[196:197], v[80:81]
	v_pk_mul_f32 v[82:83], v[198:199], v[82:83]
	v_pk_mul_f32 v[84:85], v[200:201], v[84:85]
	v_pk_mul_f32 v[86:87], v[202:203], v[86:87]
	s_nop 1
	v_mov_b32_dpp v244, v80 quad_perm:[0,0,1,1] row_mask:0xf bank_mask:0xf
	v_mov_b32_dpp v15, v84 quad_perm:[0,0,1,1] row_mask:0xf bank_mask:0xf
	v_cndmask_b32_e32 v244, v244, v15, vcc
	v_mov_b32_dpp v245, v81 quad_perm:[0,0,1,1] row_mask:0xf bank_mask:0xf
	v_mov_b32_dpp v15, v85 quad_perm:[0,0,1,1] row_mask:0xf bank_mask:0xf
	v_cndmask_b32_e32 v245, v245, v15, vcc
	v_mov_b32_dpp v246, v82 quad_perm:[0,0,1,1] row_mask:0xf bank_mask:0xf
	v_mov_b32_dpp v15, v86 quad_perm:[0,0,1,1] row_mask:0xf bank_mask:0xf
	v_cndmask_b32_e32 v246, v246, v15, vcc
	v_mov_b32_dpp v247, v83 quad_perm:[0,0,1,1] row_mask:0xf bank_mask:0xf
	v_mov_b32_dpp v15, v87 quad_perm:[0,0,1,1] row_mask:0xf bank_mask:0xf
	v_cndmask_b32_e32 v247, v247, v15, vcc
	v_mov_b32_dpp v248, v80 quad_perm:[2,2,3,3] row_mask:0xf bank_mask:0xf
	v_mov_b32_dpp v15, v84 quad_perm:[2,2,3,3] row_mask:0xf bank_mask:0xf
	v_cndmask_b32_e32 v248, v248, v15, vcc
	v_mov_b32_dpp v249, v81 quad_perm:[2,2,3,3] row_mask:0xf bank_mask:0xf
	v_mov_b32_dpp v15, v85 quad_perm:[2,2,3,3] row_mask:0xf bank_mask:0xf
	v_cndmask_b32_e32 v249, v249, v15, vcc
	v_mov_b32_dpp v250, v82 quad_perm:[2,2,3,3] row_mask:0xf bank_mask:0xf
	v_mov_b32_dpp v15, v86 quad_perm:[2,2,3,3] row_mask:0xf bank_mask:0xf
	v_cndmask_b32_e32 v250, v250, v15, vcc
	v_mov_b32_dpp v251, v83 quad_perm:[2,2,3,3] row_mask:0xf bank_mask:0xf
	v_mov_b32_dpp v15, v87 quad_perm:[2,2,3,3] row_mask:0xf bank_mask:0xf
	v_cndmask_b32_e32 v251, v251, v15, vcc
	global_store_dwordx4 v5, v[244:247], s[20:21]
	global_store_dwordx4 v5, v[248:251], s[20:21] offset:64
	s_waitcnt vmcnt(28)
	v_lshlrev_b32_e32 v88, 16, v68
	v_and_b32_e32 v89, 0xffff0000, v68
	v_lshlrev_b32_e32 v90, 16, v69
	v_and_b32_e32 v91, 0xffff0000, v69
	v_lshlrev_b32_e32 v92, 16, v70
	v_and_b32_e32 v93, 0xffff0000, v70
	v_lshlrev_b32_e32 v94, 16, v71
	v_and_b32_e32 v95, 0xffff0000, v71
	v_pk_mul_f32 v[88:89], v[10:11], v[88:89]
	v_pk_mul_f32 v[90:91], v[10:11], v[90:91]
	v_pk_mul_f32 v[92:93], v[10:11], v[92:93]
	v_pk_mul_f32 v[94:95], v[10:11], v[94:95]
	v_pk_mul_f32 v[88:89], v[204:205], v[88:89]
	v_pk_mul_f32 v[90:91], v[206:207], v[90:91]
	v_pk_mul_f32 v[92:93], v[208:209], v[92:93]
	v_pk_mul_f32 v[94:95], v[210:211], v[94:95]
	s_nop 1
	v_mov_b32_dpp v244, v88 quad_perm:[0,0,1,1] row_mask:0xf bank_mask:0xf
	v_mov_b32_dpp v15, v92 quad_perm:[0,0,1,1] row_mask:0xf bank_mask:0xf
	v_cndmask_b32_e32 v244, v244, v15, vcc
	v_mov_b32_dpp v245, v89 quad_perm:[0,0,1,1] row_mask:0xf bank_mask:0xf
	v_mov_b32_dpp v15, v93 quad_perm:[0,0,1,1] row_mask:0xf bank_mask:0xf
	v_cndmask_b32_e32 v245, v245, v15, vcc
	v_mov_b32_dpp v246, v90 quad_perm:[0,0,1,1] row_mask:0xf bank_mask:0xf
	v_mov_b32_dpp v15, v94 quad_perm:[0,0,1,1] row_mask:0xf bank_mask:0xf
	v_cndmask_b32_e32 v246, v246, v15, vcc
	v_mov_b32_dpp v247, v91 quad_perm:[0,0,1,1] row_mask:0xf bank_mask:0xf
	v_mov_b32_dpp v15, v95 quad_perm:[0,0,1,1] row_mask:0xf bank_mask:0xf
	v_cndmask_b32_e32 v247, v247, v15, vcc
	v_mov_b32_dpp v248, v88 quad_perm:[2,2,3,3] row_mask:0xf bank_mask:0xf
	v_mov_b32_dpp v15, v92 quad_perm:[2,2,3,3] row_mask:0xf bank_mask:0xf
	v_cndmask_b32_e32 v248, v248, v15, vcc
	v_mov_b32_dpp v249, v89 quad_perm:[2,2,3,3] row_mask:0xf bank_mask:0xf
	v_mov_b32_dpp v15, v93 quad_perm:[2,2,3,3] row_mask:0xf bank_mask:0xf
	v_cndmask_b32_e32 v249, v249, v15, vcc
	v_mov_b32_dpp v250, v90 quad_perm:[2,2,3,3] row_mask:0xf bank_mask:0xf
	v_mov_b32_dpp v15, v94 quad_perm:[2,2,3,3] row_mask:0xf bank_mask:0xf
	v_cndmask_b32_e32 v250, v250, v15, vcc
	v_mov_b32_dpp v251, v91 quad_perm:[2,2,3,3] row_mask:0xf bank_mask:0xf
	v_mov_b32_dpp v15, v95 quad_perm:[2,2,3,3] row_mask:0xf bank_mask:0xf
	v_cndmask_b32_e32 v251, v251, v15, vcc
	global_store_dwordx4 v5, v[244:247], s[20:21] offset:1024
	global_store_dwordx4 v5, v[248:251], s[20:21] offset:1088
	s_waitcnt vmcnt(29)
	v_lshlrev_b32_e32 v80, 16, v72
	v_and_b32_e32 v81, 0xffff0000, v72
	v_lshlrev_b32_e32 v82, 16, v73
	v_and_b32_e32 v83, 0xffff0000, v73
	v_lshlrev_b32_e32 v84, 16, v74
	v_and_b32_e32 v85, 0xffff0000, v74
	v_lshlrev_b32_e32 v86, 16, v75
	v_and_b32_e32 v87, 0xffff0000, v75
	v_pk_mul_f32 v[80:81], v[10:11], v[80:81]
	v_pk_mul_f32 v[82:83], v[10:11], v[82:83]
	v_pk_mul_f32 v[84:85], v[10:11], v[84:85]
	v_pk_mul_f32 v[86:87], v[10:11], v[86:87]
	v_pk_mul_f32 v[80:81], v[212:213], v[80:81]
	v_pk_mul_f32 v[82:83], v[214:215], v[82:83]
	v_pk_mul_f32 v[84:85], v[216:217], v[84:85]
	v_pk_mul_f32 v[86:87], v[218:219], v[86:87]
	s_nop 1
	v_mov_b32_dpp v244, v80 quad_perm:[0,0,1,1] row_mask:0xf bank_mask:0xf
	v_mov_b32_dpp v15, v84 quad_perm:[0,0,1,1] row_mask:0xf bank_mask:0xf
	v_cndmask_b32_e32 v244, v244, v15, vcc
	v_mov_b32_dpp v245, v81 quad_perm:[0,0,1,1] row_mask:0xf bank_mask:0xf
	v_mov_b32_dpp v15, v85 quad_perm:[0,0,1,1] row_mask:0xf bank_mask:0xf
	v_cndmask_b32_e32 v245, v245, v15, vcc
	v_mov_b32_dpp v246, v82 quad_perm:[0,0,1,1] row_mask:0xf bank_mask:0xf
	v_mov_b32_dpp v15, v86 quad_perm:[0,0,1,1] row_mask:0xf bank_mask:0xf
	v_cndmask_b32_e32 v246, v246, v15, vcc
	v_mov_b32_dpp v247, v83 quad_perm:[0,0,1,1] row_mask:0xf bank_mask:0xf
	v_mov_b32_dpp v15, v87 quad_perm:[0,0,1,1] row_mask:0xf bank_mask:0xf
	v_cndmask_b32_e32 v247, v247, v15, vcc
	v_mov_b32_dpp v248, v80 quad_perm:[2,2,3,3] row_mask:0xf bank_mask:0xf
	v_mov_b32_dpp v15, v84 quad_perm:[2,2,3,3] row_mask:0xf bank_mask:0xf
	v_cndmask_b32_e32 v248, v248, v15, vcc
	v_mov_b32_dpp v249, v81 quad_perm:[2,2,3,3] row_mask:0xf bank_mask:0xf
	v_mov_b32_dpp v15, v85 quad_perm:[2,2,3,3] row_mask:0xf bank_mask:0xf
	v_cndmask_b32_e32 v249, v249, v15, vcc
	v_mov_b32_dpp v250, v82 quad_perm:[2,2,3,3] row_mask:0xf bank_mask:0xf
	v_mov_b32_dpp v15, v86 quad_perm:[2,2,3,3] row_mask:0xf bank_mask:0xf
	v_cndmask_b32_e32 v250, v250, v15, vcc
	v_mov_b32_dpp v251, v83 quad_perm:[2,2,3,3] row_mask:0xf bank_mask:0xf
	v_mov_b32_dpp v15, v87 quad_perm:[2,2,3,3] row_mask:0xf bank_mask:0xf
	v_cndmask_b32_e32 v251, v251, v15, vcc
	global_store_dwordx4 v5, v[244:247], s[20:21] offset:2048
	global_store_dwordx4 v5, v[248:251], s[20:21] offset:2112
	s_waitcnt vmcnt(30)
	v_lshlrev_b32_e32 v88, 16, v76
	v_and_b32_e32 v89, 0xffff0000, v76
	v_lshlrev_b32_e32 v90, 16, v77
	v_and_b32_e32 v91, 0xffff0000, v77
	v_lshlrev_b32_e32 v92, 16, v78
	v_and_b32_e32 v93, 0xffff0000, v78
	v_lshlrev_b32_e32 v94, 16, v79
	v_and_b32_e32 v95, 0xffff0000, v79
	v_pk_mul_f32 v[88:89], v[10:11], v[88:89]
	v_pk_mul_f32 v[90:91], v[10:11], v[90:91]
	v_pk_mul_f32 v[92:93], v[10:11], v[92:93]
	v_pk_mul_f32 v[94:95], v[10:11], v[94:95]
	v_pk_mul_f32 v[88:89], v[220:221], v[88:89]
	v_pk_mul_f32 v[90:91], v[222:223], v[90:91]
	v_pk_mul_f32 v[92:93], v[224:225], v[92:93]
	v_pk_mul_f32 v[94:95], v[226:227], v[94:95]
	s_nop 1
	v_mov_b32_dpp v244, v88 quad_perm:[0,0,1,1] row_mask:0xf bank_mask:0xf
	v_mov_b32_dpp v15, v92 quad_perm:[0,0,1,1] row_mask:0xf bank_mask:0xf
	v_cndmask_b32_e32 v244, v244, v15, vcc
	v_mov_b32_dpp v245, v89 quad_perm:[0,0,1,1] row_mask:0xf bank_mask:0xf
	v_mov_b32_dpp v15, v93 quad_perm:[0,0,1,1] row_mask:0xf bank_mask:0xf
	v_cndmask_b32_e32 v245, v245, v15, vcc
	v_mov_b32_dpp v246, v90 quad_perm:[0,0,1,1] row_mask:0xf bank_mask:0xf
	v_mov_b32_dpp v15, v94 quad_perm:[0,0,1,1] row_mask:0xf bank_mask:0xf
	v_cndmask_b32_e32 v246, v246, v15, vcc
	v_mov_b32_dpp v247, v91 quad_perm:[0,0,1,1] row_mask:0xf bank_mask:0xf
	v_mov_b32_dpp v15, v95 quad_perm:[0,0,1,1] row_mask:0xf bank_mask:0xf
	v_cndmask_b32_e32 v247, v247, v15, vcc
	v_mov_b32_dpp v248, v88 quad_perm:[2,2,3,3] row_mask:0xf bank_mask:0xf
	v_mov_b32_dpp v15, v92 quad_perm:[2,2,3,3] row_mask:0xf bank_mask:0xf
	v_cndmask_b32_e32 v248, v248, v15, vcc
	v_mov_b32_dpp v249, v89 quad_perm:[2,2,3,3] row_mask:0xf bank_mask:0xf
	v_mov_b32_dpp v15, v93 quad_perm:[2,2,3,3] row_mask:0xf bank_mask:0xf
	v_cndmask_b32_e32 v249, v249, v15, vcc
	v_mov_b32_dpp v250, v90 quad_perm:[2,2,3,3] row_mask:0xf bank_mask:0xf
	v_mov_b32_dpp v15, v94 quad_perm:[2,2,3,3] row_mask:0xf bank_mask:0xf
	v_cndmask_b32_e32 v250, v250, v15, vcc
	v_mov_b32_dpp v251, v91 quad_perm:[2,2,3,3] row_mask:0xf bank_mask:0xf
	v_mov_b32_dpp v15, v95 quad_perm:[2,2,3,3] row_mask:0xf bank_mask:0xf
	v_cndmask_b32_e32 v251, v251, v15, vcc
	global_store_dwordx4 v5, v[244:247], s[20:21] offset:3072
	global_store_dwordx4 v5, v[248:251], s[20:21] offset:3136
	s_add_i32 s28, s28, s66
	s_cmpk_gt_i32 s28, 0x2fff
	s_cbranch_scc0 .Lp12_row
